# dense FFN down-projection epilogue (EpiYLN, fp8 GEMM) software-pipelined like the attention-output projection epilogue
# baseline (speedup 1.0000x reference)
; __device__ __forceinline__ f32x4 ld4h(const ystream_t* p) { return __builtin_convertvector(*(const h16x4*)p, f32x4); }
; __device__ __forceinline__ void st4h(ystream_t* p, f32x4 v) { *(h16x4*)p = __builtin_convertvector(v, h16x4); }
;     __device__ __forceinline__ void operator()(const f32x4 (&acc)[2][2][4][2], const Unit& u, int wr, int wc, int fr, int fq) const {
;         const int row0 = u.pm * BM + wr * 64 + fr, colb = u.pn * BM + wc * 32 + 4 * fq;
; #pragma unroll
;         for (int ai = 0; ai < 2; ++ai)
; #pragma unroll
;             for (int m = 0; m < 4; ++m) {
;                 const int row = row0 + ai * HALF + m * 16;
;                 const float mu = st[(size_t)row * 32 + so], rs = st[(size_t)row * 32 + so + 1];
;                 const size_t off = (size_t)row * DM + colb;
; #pragma unroll
;                 for (int bj = 0; bj < 2; ++bj)
; #pragma unroll
;                     for (int n = 0; n < 2; ++n) { const int c = colb + bj * HALF + n * 16;
;                         const f32x4 gv = *(const f32x4*)(g + c), bv = *(const f32x4*)(b + c), yv = ld4h(Y + off + bj * HALF + n * 16);
;                         st4h(Y + off + bj * HALF + n * 16, ((yv - mu) * rs * gv + bv) * DN_ALPHA + acc[ai][bj][m][n] * asc); }
;                 asm volatile("" ::: "memory");
;             }
;     }
.LBB0_1618:
	v_lshl_add_u32 v30, s21, 8, v194
	v_lshl_or_b32 v32, s29, 8, v196
	v_ashrrev_i32_e32 v31, 31, v30
	v_ashrrev_i32_e32 v33, 31, v32
	v_lshlrev_b64 v[18:19], 11, v[30:31]
	v_lshlrev_b64 v[20:21], 7, v[30:31]
	v_lshl_add_u64 v[18:19], s[4:5], 0, v[18:19]
	v_lshl_add_u64 v[20:21], s[6:7], 0, v[20:21]
	v_lshl_add_u64 v[18:19], v[32:33], 1, v[18:19]
	v_lshl_add_u64 v[34:35], v[32:33], 2, s[8:9]
	v_lshl_add_u64 v[36:37], v[32:33], 2, s[10:11]
	s_nop 15
	s_nop 15
	s_nop 15
	global_load_dwordx2 v[212:213], v[20:21], off offset:80
	global_load_dwordx2 v[170:171], v[18:19], off
	global_load_dwordx2 v[176:177], v[18:19], off offset:32
	global_load_dwordx2 v[208:209], v[18:19], off offset:256
	global_load_dwordx2 v[210:211], v[18:19], off offset:288
	global_load_dwordx4 v[38:41], v[34:35], off offset:0
	global_load_dwordx4 v[58:61], v[36:37], off offset:0
	global_load_dwordx4 v[42:45], v[34:35], off offset:64
	global_load_dwordx4 v[66:69], v[36:37], off offset:64
	global_load_dwordx4 v[46:49], v[34:35], off offset:512
	global_load_dwordx4 v[74:77], v[36:37], off offset:512
	global_load_dwordx4 v[50:53], v[34:35], off offset:576
	global_load_dwordx4 v[122:125], v[36:37], off offset:576
	s_mov_b64 s[100:101], 0x8000
	v_lshl_add_u64 v[30:31], v[18:19], 0, s[100:101]
	global_load_dwordx2 v[222:223], v[20:21], off offset:2128
	global_load_dwordx2 v[214:215], v[30:31], off
	global_load_dwordx2 v[216:217], v[30:31], off offset:32
	global_load_dwordx2 v[218:219], v[30:31], off offset:256
	global_load_dwordx2 v[220:221], v[30:31], off offset:288
	s_mov_b64 s[100:101], 0x10000
	v_lshl_add_u64 v[30:31], v[18:19], 0, s[100:101]
	s_mov_b64 s[100:101], 0x1000
	v_lshl_add_u64 v[232:233], v[20:21], 0, s[100:101]
	global_load_dwordx2 v[232:233], v[232:233], off offset:80
	global_load_dwordx2 v[224:225], v[30:31], off
	global_load_dwordx2 v[226:227], v[30:31], off offset:32
	global_load_dwordx2 v[228:229], v[30:31], off offset:256
	global_load_dwordx2 v[230:231], v[30:31], off offset:288
	s_mov_b64 s[100:101], 0x18000
	v_lshl_add_u64 v[30:31], v[18:19], 0, s[100:101]
	s_mov_b64 s[100:101], 0x1800
	v_lshl_add_u64 v[242:243], v[20:21], 0, s[100:101]
	global_load_dwordx2 v[242:243], v[242:243], off offset:80
	global_load_dwordx2 v[234:235], v[30:31], off
	global_load_dwordx2 v[236:237], v[30:31], off offset:32
	global_load_dwordx2 v[238:239], v[30:31], off offset:256
	global_load_dwordx2 v[240:241], v[30:31], off offset:288
	s_waitcnt vmcnt(21)
	v_cvt_f32_f16_e32 v34, v170
	v_cvt_f32_f16_sdwa v35, v170 dst_sel:DWORD dst_unused:UNUSED_PAD src0_sel:WORD_1
	v_cvt_f32_f16_e32 v36, v171
	v_cvt_f32_f16_sdwa v37, v171 dst_sel:DWORD dst_unused:UNUSED_PAD src0_sel:WORD_1
	v_sub_f32_e32 v34, v34, v212
	v_sub_f32_e32 v35, v35, v212
	v_sub_f32_e32 v36, v36, v212
	v_sub_f32_e32 v37, v37, v212
	v_pk_mul_f32 v[34:35], v[212:213], v[34:35] op_sel:[1,0]
	v_pk_mul_f32 v[36:37], v[212:213], v[36:37] op_sel:[1,0]
	v_pk_fma_f32 v[34:35], v[38:39], v[34:35], v[58:59]
	v_pk_fma_f32 v[36:37], v[40:41], v[36:37], v[60:61]
	v_pk_fma_f32 v[192:193], v[34:35], s[36:37], v[192:193] op_sel_hi:[1,0,1]
	v_pk_fma_f32 v[190:191], v[36:37], s[36:37], v[190:191] op_sel_hi:[1,0,1]
	s_nop 0
	v_cvt_pk_f16_f32 v191, v190, v191
	v_cvt_pk_f16_f32 v190, v192, v193
	global_store_dwordx2 v[18:19], v[190:191], off
	s_waitcnt vmcnt(20)
	v_cvt_f32_f16_e32 v34, v176
	v_cvt_f32_f16_sdwa v35, v176 dst_sel:DWORD dst_unused:UNUSED_PAD src0_sel:WORD_1
	v_cvt_f32_f16_e32 v36, v177
	v_cvt_f32_f16_sdwa v37, v177 dst_sel:DWORD dst_unused:UNUSED_PAD src0_sel:WORD_1
	v_sub_f32_e32 v34, v34, v212
	v_sub_f32_e32 v35, v35, v212
	v_sub_f32_e32 v36, v36, v212
	v_sub_f32_e32 v37, v37, v212
	v_pk_mul_f32 v[34:35], v[212:213], v[34:35] op_sel:[1,0]
	v_pk_mul_f32 v[36:37], v[212:213], v[36:37] op_sel:[1,0]
	v_pk_fma_f32 v[34:35], v[42:43], v[34:35], v[66:67]
	v_pk_fma_f32 v[36:37], v[44:45], v[36:37], v[68:69]
	v_pk_fma_f32 v[188:189], v[34:35], s[36:37], v[188:189] op_sel_hi:[1,0,1]
	v_pk_fma_f32 v[186:187], v[36:37], s[36:37], v[186:187] op_sel_hi:[1,0,1]
	s_nop 0
	v_cvt_pk_f16_f32 v187, v186, v187
	v_cvt_pk_f16_f32 v186, v188, v189
	global_store_dwordx2 v[18:19], v[186:187], off offset:32
	s_waitcnt vmcnt(19)
	v_cvt_f32_f16_e32 v34, v208
	v_cvt_f32_f16_sdwa v35, v208 dst_sel:DWORD dst_unused:UNUSED_PAD src0_sel:WORD_1
	v_cvt_f32_f16_e32 v36, v209
	v_cvt_f32_f16_sdwa v37, v209 dst_sel:DWORD dst_unused:UNUSED_PAD src0_sel:WORD_1
	v_sub_f32_e32 v34, v34, v212
	v_sub_f32_e32 v35, v35, v212
	v_sub_f32_e32 v36, v36, v212
	v_sub_f32_e32 v37, v37, v212
	v_pk_mul_f32 v[34:35], v[212:213], v[34:35] op_sel:[1,0]
	v_pk_mul_f32 v[36:37], v[212:213], v[36:37] op_sel:[1,0]
	v_pk_fma_f32 v[34:35], v[46:47], v[34:35], v[74:75]
	v_pk_fma_f32 v[36:37], v[48:49], v[36:37], v[76:77]
	v_pk_fma_f32 v[184:185], v[34:35], s[36:37], v[184:185] op_sel_hi:[1,0,1]
	v_pk_fma_f32 v[182:183], v[36:37], s[36:37], v[182:183] op_sel_hi:[1,0,1]
	s_nop 0
	v_cvt_pk_f16_f32 v183, v182, v183
	v_cvt_pk_f16_f32 v182, v184, v185
	global_store_dwordx2 v[18:19], v[182:183], off offset:256
	s_waitcnt vmcnt(18)
; __device__ __forceinline__ f32x4 ld4h(const ystream_t* p) { return __builtin_convertvector(*(const h16x4*)p, f32x4); }
; __device__ __forceinline__ void st4h(ystream_t* p, f32x4 v) { *(h16x4*)p = __builtin_convertvector(v, h16x4); }
;     __device__ __forceinline__ void operator()(const f32x4 (&acc)[2][2][4][2], const Unit& u, int wr, int wc, int fr, int fq) const {
;         const int row0 = u.pm * BM + wr * 64 + fr, colb = u.pn * BM + wc * 32 + 4 * fq;
; #pragma unroll
;         for (int ai = 0; ai < 2; ++ai)
; #pragma unroll
;             for (int m = 0; m < 4; ++m) {
;                 const int row = row0 + ai * HALF + m * 16;
;                 const float mu = st[(size_t)row * 32 + so], rs = st[(size_t)row * 32 + so + 1];
;                 const size_t off = (size_t)row * DM + colb;
; #pragma unroll
;                 for (int bj = 0; bj < 2; ++bj)
; #pragma unroll
;                     for (int n = 0; n < 2; ++n) { const int c = colb + bj * HALF + n * 16;
;                         const f32x4 gv = *(const f32x4*)(g + c), bv = *(const f32x4*)(b + c), yv = ld4h(Y + off + bj * HALF + n * 16);
;                         st4h(Y + off + bj * HALF + n * 16, ((yv - mu) * rs * gv + bv) * DN_ALPHA + acc[ai][bj][m][n] * asc); }
;                 asm volatile("" ::: "memory");
;             }
;     }
	v_cvt_f32_f16_e32 v34, v210
	v_cvt_f32_f16_sdwa v35, v210 dst_sel:DWORD dst_unused:UNUSED_PAD src0_sel:WORD_1
	v_cvt_f32_f16_e32 v36, v211
	v_cvt_f32_f16_sdwa v37, v211 dst_sel:DWORD dst_unused:UNUSED_PAD src0_sel:WORD_1
	v_sub_f32_e32 v34, v34, v212
	v_sub_f32_e32 v35, v35, v212
	v_sub_f32_e32 v36, v36, v212
	v_sub_f32_e32 v37, v37, v212
	v_pk_mul_f32 v[34:35], v[212:213], v[34:35] op_sel:[1,0]
	v_pk_mul_f32 v[36:37], v[212:213], v[36:37] op_sel:[1,0]
	v_pk_fma_f32 v[34:35], v[50:51], v[34:35], v[122:123]
	v_pk_fma_f32 v[36:37], v[52:53], v[36:37], v[124:125]
	v_pk_fma_f32 v[160:161], v[34:35], s[36:37], v[160:161] op_sel_hi:[1,0,1]
	v_pk_fma_f32 v[158:159], v[36:37], s[36:37], v[158:159] op_sel_hi:[1,0,1]
	s_nop 0
	v_cvt_pk_f16_f32 v159, v158, v159
	v_cvt_pk_f16_f32 v158, v160, v161
	global_store_dwordx2 v[18:19], v[158:159], off offset:288
	s_mov_b64 s[100:101], 0x40000
	v_lshl_add_u64 v[30:31], v[18:19], 0, s[100:101]
	s_mov_b64 s[100:101], 0x4000
	v_lshl_add_u64 v[182:183], v[20:21], 0, s[100:101]
	global_load_dwordx2 v[182:183], v[182:183], off offset:80
	global_load_dwordx2 v[158:159], v[30:31], off
	global_load_dwordx2 v[160:161], v[30:31], off offset:32
	global_load_dwordx2 v[170:171], v[30:31], off offset:256
	global_load_dwordx2 v[176:177], v[30:31], off offset:288
	s_mov_b64 s[100:101], 0x48000
	v_lshl_add_u64 v[30:31], v[18:19], 0, s[100:101]
	s_mov_b64 s[100:101], 0x4800
	v_lshl_add_u64 v[192:193], v[20:21], 0, s[100:101]
	global_load_dwordx2 v[192:193], v[192:193], off offset:80
	global_load_dwordx2 v[184:185], v[30:31], off
	global_load_dwordx2 v[186:187], v[30:31], off offset:32
	global_load_dwordx2 v[188:189], v[30:31], off offset:256
	global_load_dwordx2 v[190:191], v[30:31], off offset:288
	s_mov_b64 s[100:101], 0x50000
	v_lshl_add_u64 v[30:31], v[18:19], 0, s[100:101]
	s_mov_b64 s[100:101], 0x5000
	v_lshl_add_u64 v[246:247], v[20:21], 0, s[100:101]
	global_load_dwordx2 v[246:247], v[246:247], off offset:80
	global_load_dwordx2 v[208:209], v[30:31], off
	global_load_dwordx2 v[210:211], v[30:31], off offset:32
	global_load_dwordx2 v[212:213], v[30:31], off offset:256
	global_load_dwordx2 v[244:245], v[30:31], off offset:288
	s_mov_b64 s[100:101], 0x8000
	v_lshl_add_u64 v[32:33], v[18:19], 0, s[100:101]
	s_waitcnt vmcnt(32)
	v_cvt_f32_f16_e32 v34, v214
	v_cvt_f32_f16_sdwa v35, v214 dst_sel:DWORD dst_unused:UNUSED_PAD src0_sel:WORD_1
	v_cvt_f32_f16_e32 v36, v215
	v_cvt_f32_f16_sdwa v37, v215 dst_sel:DWORD dst_unused:UNUSED_PAD src0_sel:WORD_1
	v_sub_f32_e32 v34, v34, v222
	v_sub_f32_e32 v35, v35, v222
	v_sub_f32_e32 v36, v36, v222
	v_sub_f32_e32 v37, v37, v222
	v_pk_mul_f32 v[34:35], v[222:223], v[34:35] op_sel:[1,0]
	v_pk_mul_f32 v[36:37], v[222:223], v[36:37] op_sel:[1,0]
	v_pk_fma_f32 v[34:35], v[38:39], v[34:35], v[58:59]
	v_pk_fma_f32 v[36:37], v[40:41], v[36:37], v[60:61]
	v_pk_fma_f32 v[156:157], v[34:35], s[36:37], v[156:157] op_sel_hi:[1,0,1]
	v_pk_fma_f32 v[154:155], v[36:37], s[36:37], v[154:155] op_sel_hi:[1,0,1]
	s_nop 0
	v_cvt_pk_f16_f32 v155, v154, v155
	v_cvt_pk_f16_f32 v154, v156, v157
	global_store_dwordx2 v[32:33], v[154:155], off
	s_waitcnt vmcnt(32)
	v_cvt_f32_f16_e32 v34, v216
	v_cvt_f32_f16_sdwa v35, v216 dst_sel:DWORD dst_unused:UNUSED_PAD src0_sel:WORD_1
	v_cvt_f32_f16_e32 v36, v217
	v_cvt_f32_f16_sdwa v37, v217 dst_sel:DWORD dst_unused:UNUSED_PAD src0_sel:WORD_1
	v_sub_f32_e32 v34, v34, v222
	v_sub_f32_e32 v35, v35, v222
	v_sub_f32_e32 v36, v36, v222
	v_sub_f32_e32 v37, v37, v222
	v_pk_mul_f32 v[34:35], v[222:223], v[34:35] op_sel:[1,0]
	v_pk_mul_f32 v[36:37], v[222:223], v[36:37] op_sel:[1,0]
	v_pk_fma_f32 v[34:35], v[42:43], v[34:35], v[66:67]
	v_pk_fma_f32 v[36:37], v[44:45], v[36:37], v[68:69]
	v_pk_fma_f32 v[152:153], v[34:35], s[36:37], v[152:153] op_sel_hi:[1,0,1]
	v_pk_fma_f32 v[150:151], v[36:37], s[36:37], v[150:151] op_sel_hi:[1,0,1]
	s_nop 0
	v_cvt_pk_f16_f32 v151, v150, v151
	v_cvt_pk_f16_f32 v150, v152, v153
	global_store_dwordx2 v[32:33], v[150:151], off offset:32
	s_waitcnt vmcnt(32)
	v_cvt_f32_f16_e32 v34, v218
	v_cvt_f32_f16_sdwa v35, v218 dst_sel:DWORD dst_unused:UNUSED_PAD src0_sel:WORD_1
	v_cvt_f32_f16_e32 v36, v219
	v_cvt_f32_f16_sdwa v37, v219 dst_sel:DWORD dst_unused:UNUSED_PAD src0_sel:WORD_1
	v_sub_f32_e32 v34, v34, v222
	v_sub_f32_e32 v35, v35, v222
	v_sub_f32_e32 v36, v36, v222
	v_sub_f32_e32 v37, v37, v222
	v_pk_mul_f32 v[34:35], v[222:223], v[34:35] op_sel:[1,0]
	v_pk_mul_f32 v[36:37], v[222:223], v[36:37] op_sel:[1,0]
	v_pk_fma_f32 v[34:35], v[46:47], v[34:35], v[74:75]
	v_pk_fma_f32 v[36:37], v[48:49], v[36:37], v[76:77]
	v_pk_fma_f32 v[148:149], v[34:35], s[36:37], v[148:149] op_sel_hi:[1,0,1]
	v_pk_fma_f32 v[146:147], v[36:37], s[36:37], v[146:147] op_sel_hi:[1,0,1]
	s_nop 0
	v_cvt_pk_f16_f32 v147, v146, v147
	v_cvt_pk_f16_f32 v146, v148, v149
	global_store_dwordx2 v[32:33], v[146:147], off offset:256
	s_waitcnt vmcnt(32)
	v_cvt_f32_f16_e32 v34, v220
	v_cvt_f32_f16_sdwa v35, v220 dst_sel:DWORD dst_unused:UNUSED_PAD src0_sel:WORD_1
	v_cvt_f32_f16_e32 v36, v221
	v_cvt_f32_f16_sdwa v37, v221 dst_sel:DWORD dst_unused:UNUSED_PAD src0_sel:WORD_1
	v_sub_f32_e32 v34, v34, v222
	v_sub_f32_e32 v35, v35, v222
	v_sub_f32_e32 v36, v36, v222
	v_sub_f32_e32 v37, v37, v222
	v_pk_mul_f32 v[34:35], v[222:223], v[34:35] op_sel:[1,0]
	v_pk_mul_f32 v[36:37], v[222:223], v[36:37] op_sel:[1,0]
	v_pk_fma_f32 v[34:35], v[50:51], v[34:35], v[122:123]
	v_pk_fma_f32 v[36:37], v[52:53], v[36:37], v[124:125]
	v_pk_fma_f32 v[144:145], v[34:35], s[36:37], v[144:145] op_sel_hi:[1,0,1]
	v_pk_fma_f32 v[142:143], v[36:37], s[36:37], v[142:143] op_sel_hi:[1,0,1]
	s_nop 0
	v_cvt_pk_f16_f32 v143, v142, v143
	v_cvt_pk_f16_f32 v142, v144, v145
	global_store_dwordx2 v[32:33], v[142:143], off offset:288
	s_mov_b64 s[100:101], 0x58000
	v_lshl_add_u64 v[30:31], v[18:19], 0, s[100:101]
	s_mov_b64 s[100:101], 0x5800
	v_lshl_add_u64 v[150:151], v[20:21], 0, s[100:101]
	global_load_dwordx2 v[150:151], v[150:151], off offset:80
	global_load_dwordx2 v[142:143], v[30:31], off
	global_load_dwordx2 v[144:145], v[30:31], off offset:32
	global_load_dwordx2 v[146:147], v[30:31], off offset:256
	global_load_dwordx2 v[148:149], v[30:31], off offset:288
	s_mov_b64 s[100:101], 0x10000
	v_lshl_add_u64 v[32:33], v[18:19], 0, s[100:101]
	s_waitcnt vmcnt(36)
; __device__ __forceinline__ f32x4 ld4h(const ystream_t* p) { return __builtin_convertvector(*(const h16x4*)p, f32x4); }
; __device__ __forceinline__ void st4h(ystream_t* p, f32x4 v) { *(h16x4*)p = __builtin_convertvector(v, h16x4); }
;     __device__ __forceinline__ void operator()(const f32x4 (&acc)[2][2][4][2], const Unit& u, int wr, int wc, int fr, int fq) const {
;         const int row0 = u.pm * BM + wr * 64 + fr, colb = u.pn * BM + wc * 32 + 4 * fq;
; #pragma unroll
;         for (int ai = 0; ai < 2; ++ai)
; #pragma unroll
;             for (int m = 0; m < 4; ++m) {
;                 const int row = row0 + ai * HALF + m * 16;
;                 const float mu = st[(size_t)row * 32 + so], rs = st[(size_t)row * 32 + so + 1];
;                 const size_t off = (size_t)row * DM + colb;
; #pragma unroll
;                 for (int bj = 0; bj < 2; ++bj)
; #pragma unroll
;                     for (int n = 0; n < 2; ++n) { const int c = colb + bj * HALF + n * 16;
;                         const f32x4 gv = *(const f32x4*)(g + c), bv = *(const f32x4*)(b + c), yv = ld4h(Y + off + bj * HALF + n * 16);
;                         st4h(Y + off + bj * HALF + n * 16, ((yv - mu) * rs * gv + bv) * DN_ALPHA + acc[ai][bj][m][n] * asc); }
;                 asm volatile("" ::: "memory");
;             }
;     }
	v_cvt_f32_f16_e32 v34, v224
	v_cvt_f32_f16_sdwa v35, v224 dst_sel:DWORD dst_unused:UNUSED_PAD src0_sel:WORD_1
	v_cvt_f32_f16_e32 v36, v225
	v_cvt_f32_f16_sdwa v37, v225 dst_sel:DWORD dst_unused:UNUSED_PAD src0_sel:WORD_1
	v_sub_f32_e32 v34, v34, v232
	v_sub_f32_e32 v35, v35, v232
	v_sub_f32_e32 v36, v36, v232
	v_sub_f32_e32 v37, v37, v232
	v_pk_mul_f32 v[34:35], v[232:233], v[34:35] op_sel:[1,0]
	v_pk_mul_f32 v[36:37], v[232:233], v[36:37] op_sel:[1,0]
	v_pk_fma_f32 v[34:35], v[38:39], v[34:35], v[58:59]
	v_pk_fma_f32 v[36:37], v[40:41], v[36:37], v[60:61]
	v_pk_fma_f32 v[138:139], v[34:35], s[36:37], v[138:139] op_sel_hi:[1,0,1]
	v_pk_fma_f32 v[140:141], v[36:37], s[36:37], v[140:141] op_sel_hi:[1,0,1]
	s_nop 0
	v_cvt_pk_f16_f32 v141, v140, v141
	v_cvt_pk_f16_f32 v140, v138, v139
	global_store_dwordx2 v[32:33], v[140:141], off
	s_waitcnt vmcnt(36)
	v_cvt_f32_f16_e32 v34, v226
	v_cvt_f32_f16_sdwa v35, v226 dst_sel:DWORD dst_unused:UNUSED_PAD src0_sel:WORD_1
	v_cvt_f32_f16_e32 v36, v227
	v_cvt_f32_f16_sdwa v37, v227 dst_sel:DWORD dst_unused:UNUSED_PAD src0_sel:WORD_1
	v_sub_f32_e32 v34, v34, v232
	v_sub_f32_e32 v35, v35, v232
	v_sub_f32_e32 v36, v36, v232
	v_sub_f32_e32 v37, v37, v232
	v_pk_mul_f32 v[34:35], v[232:233], v[34:35] op_sel:[1,0]
	v_pk_mul_f32 v[36:37], v[232:233], v[36:37] op_sel:[1,0]
	v_pk_fma_f32 v[34:35], v[42:43], v[34:35], v[66:67]
	v_pk_fma_f32 v[36:37], v[44:45], v[36:37], v[68:69]
	v_pk_fma_f32 v[136:137], v[34:35], s[36:37], v[136:137] op_sel_hi:[1,0,1]
	v_pk_fma_f32 v[134:135], v[36:37], s[36:37], v[134:135] op_sel_hi:[1,0,1]
	s_nop 0
	v_cvt_pk_f16_f32 v135, v134, v135
	v_cvt_pk_f16_f32 v134, v136, v137
	global_store_dwordx2 v[32:33], v[134:135], off offset:32
	s_waitcnt vmcnt(36)
	v_cvt_f32_f16_e32 v34, v228
	v_cvt_f32_f16_sdwa v35, v228 dst_sel:DWORD dst_unused:UNUSED_PAD src0_sel:WORD_1
	v_cvt_f32_f16_e32 v36, v229
	v_cvt_f32_f16_sdwa v37, v229 dst_sel:DWORD dst_unused:UNUSED_PAD src0_sel:WORD_1
	v_sub_f32_e32 v34, v34, v232
	v_sub_f32_e32 v35, v35, v232
	v_sub_f32_e32 v36, v36, v232
	v_sub_f32_e32 v37, v37, v232
	v_pk_mul_f32 v[34:35], v[232:233], v[34:35] op_sel:[1,0]
	v_pk_mul_f32 v[36:37], v[232:233], v[36:37] op_sel:[1,0]
	v_pk_fma_f32 v[34:35], v[46:47], v[34:35], v[74:75]
	v_pk_fma_f32 v[36:37], v[48:49], v[36:37], v[76:77]
	v_pk_fma_f32 v[132:133], v[34:35], s[36:37], v[132:133] op_sel_hi:[1,0,1]
	v_pk_fma_f32 v[130:131], v[36:37], s[36:37], v[130:131] op_sel_hi:[1,0,1]
	s_nop 0
	v_cvt_pk_f16_f32 v131, v130, v131
	v_cvt_pk_f16_f32 v130, v132, v133
	global_store_dwordx2 v[32:33], v[130:131], off offset:256
	s_waitcnt vmcnt(36)
	v_cvt_f32_f16_e32 v34, v230
	v_cvt_f32_f16_sdwa v35, v230 dst_sel:DWORD dst_unused:UNUSED_PAD src0_sel:WORD_1
	v_cvt_f32_f16_e32 v36, v231
	v_cvt_f32_f16_sdwa v37, v231 dst_sel:DWORD dst_unused:UNUSED_PAD src0_sel:WORD_1
	v_sub_f32_e32 v34, v34, v232
	v_sub_f32_e32 v35, v35, v232
	v_sub_f32_e32 v36, v36, v232
	v_sub_f32_e32 v37, v37, v232
	v_pk_mul_f32 v[34:35], v[232:233], v[34:35] op_sel:[1,0]
	v_pk_mul_f32 v[36:37], v[232:233], v[36:37] op_sel:[1,0]
	v_pk_fma_f32 v[34:35], v[50:51], v[34:35], v[122:123]
	v_pk_fma_f32 v[36:37], v[52:53], v[36:37], v[124:125]
	v_pk_fma_f32 v[128:129], v[34:35], s[36:37], v[128:129] op_sel_hi:[1,0,1]
	v_pk_fma_f32 v[126:127], v[36:37], s[36:37], v[126:127] op_sel_hi:[1,0,1]
	s_nop 0
	v_cvt_pk_f16_f32 v127, v126, v127
	v_cvt_pk_f16_f32 v126, v128, v129
	global_store_dwordx2 v[32:33], v[126:127], off offset:288
	s_mov_b64 s[100:101], 0x18000
	v_lshl_add_u64 v[32:33], v[18:19], 0, s[100:101]
	s_waitcnt vmcnt(35)
	v_cvt_f32_f16_e32 v34, v234
	v_cvt_f32_f16_sdwa v35, v234 dst_sel:DWORD dst_unused:UNUSED_PAD src0_sel:WORD_1
	v_cvt_f32_f16_e32 v36, v235
	v_cvt_f32_f16_sdwa v37, v235 dst_sel:DWORD dst_unused:UNUSED_PAD src0_sel:WORD_1
	v_sub_f32_e32 v34, v34, v242
	v_sub_f32_e32 v35, v35, v242
	v_sub_f32_e32 v36, v36, v242
	v_sub_f32_e32 v37, v37, v242
	v_pk_mul_f32 v[34:35], v[242:243], v[34:35] op_sel:[1,0]
	v_pk_mul_f32 v[36:37], v[242:243], v[36:37] op_sel:[1,0]
	v_pk_fma_f32 v[34:35], v[38:39], v[34:35], v[58:59]
	v_pk_fma_f32 v[36:37], v[40:41], v[36:37], v[60:61]
	v_pk_fma_f32 v[120:121], v[34:35], s[36:37], v[120:121] op_sel_hi:[1,0,1]
	v_pk_fma_f32 v[118:119], v[36:37], s[36:37], v[118:119] op_sel_hi:[1,0,1]
	s_nop 0
	v_cvt_pk_f16_f32 v119, v118, v119
	v_cvt_pk_f16_f32 v118, v120, v121
	global_store_dwordx2 v[32:33], v[118:119], off
	s_waitcnt vmcnt(35)
	v_cvt_f32_f16_e32 v34, v236
	v_cvt_f32_f16_sdwa v35, v236 dst_sel:DWORD dst_unused:UNUSED_PAD src0_sel:WORD_1
	v_cvt_f32_f16_e32 v36, v237
	v_cvt_f32_f16_sdwa v37, v237 dst_sel:DWORD dst_unused:UNUSED_PAD src0_sel:WORD_1
	v_sub_f32_e32 v34, v34, v242
	v_sub_f32_e32 v35, v35, v242
	v_sub_f32_e32 v36, v36, v242
	v_sub_f32_e32 v37, v37, v242
	v_pk_mul_f32 v[34:35], v[242:243], v[34:35] op_sel:[1,0]
	v_pk_mul_f32 v[36:37], v[242:243], v[36:37] op_sel:[1,0]
	v_pk_fma_f32 v[34:35], v[42:43], v[34:35], v[66:67]
	v_pk_fma_f32 v[36:37], v[44:45], v[36:37], v[68:69]
	v_pk_fma_f32 v[114:115], v[34:35], s[36:37], v[114:115] op_sel_hi:[1,0,1]
	v_pk_fma_f32 v[116:117], v[36:37], s[36:37], v[116:117] op_sel_hi:[1,0,1]
	s_nop 0
	v_cvt_pk_f16_f32 v117, v116, v117
	v_cvt_pk_f16_f32 v116, v114, v115
	global_store_dwordx2 v[32:33], v[116:117], off offset:32
	s_waitcnt vmcnt(35)
; __device__ __forceinline__ f32x4 ld4h(const ystream_t* p) { return __builtin_convertvector(*(const h16x4*)p, f32x4); }
; __device__ __forceinline__ void st4h(ystream_t* p, f32x4 v) { *(h16x4*)p = __builtin_convertvector(v, h16x4); }
;     __device__ __forceinline__ void operator()(const f32x4 (&acc)[2][2][4][2], const Unit& u, int wr, int wc, int fr, int fq) const {
;         const int row0 = u.pm * BM + wr * 64 + fr, colb = u.pn * BM + wc * 32 + 4 * fq;
; #pragma unroll
;         for (int ai = 0; ai < 2; ++ai)
; #pragma unroll
;             for (int m = 0; m < 4; ++m) {
;                 const int row = row0 + ai * HALF + m * 16;
;                 const float mu = st[(size_t)row * 32 + so], rs = st[(size_t)row * 32 + so + 1];
;                 const size_t off = (size_t)row * DM + colb;
; #pragma unroll
;                 for (int bj = 0; bj < 2; ++bj)
; #pragma unroll
;                     for (int n = 0; n < 2; ++n) { const int c = colb + bj * HALF + n * 16;
;                         const f32x4 gv = *(const f32x4*)(g + c), bv = *(const f32x4*)(b + c), yv = ld4h(Y + off + bj * HALF + n * 16);
;                         st4h(Y + off + bj * HALF + n * 16, ((yv - mu) * rs * gv + bv) * DN_ALPHA + acc[ai][bj][m][n] * asc); }
;                 asm volatile("" ::: "memory");
;             }
;     }
	v_cvt_f32_f16_e32 v34, v238
	v_cvt_f32_f16_sdwa v35, v238 dst_sel:DWORD dst_unused:UNUSED_PAD src0_sel:WORD_1
	v_cvt_f32_f16_e32 v36, v239
	v_cvt_f32_f16_sdwa v37, v239 dst_sel:DWORD dst_unused:UNUSED_PAD src0_sel:WORD_1
	v_sub_f32_e32 v34, v34, v242
	v_sub_f32_e32 v35, v35, v242
	v_sub_f32_e32 v36, v36, v242
	v_sub_f32_e32 v37, v37, v242
	v_pk_mul_f32 v[34:35], v[242:243], v[34:35] op_sel:[1,0]
	v_pk_mul_f32 v[36:37], v[242:243], v[36:37] op_sel:[1,0]
	v_pk_fma_f32 v[34:35], v[46:47], v[34:35], v[74:75]
	v_pk_fma_f32 v[36:37], v[48:49], v[36:37], v[76:77]
	v_pk_fma_f32 v[112:113], v[34:35], s[36:37], v[112:113] op_sel_hi:[1,0,1]
	v_pk_fma_f32 v[110:111], v[36:37], s[36:37], v[110:111] op_sel_hi:[1,0,1]
	s_nop 0
	v_cvt_pk_f16_f32 v111, v110, v111
	v_cvt_pk_f16_f32 v110, v112, v113
	global_store_dwordx2 v[32:33], v[110:111], off offset:256
	s_waitcnt vmcnt(35)
	v_cvt_f32_f16_e32 v34, v240
	v_cvt_f32_f16_sdwa v35, v240 dst_sel:DWORD dst_unused:UNUSED_PAD src0_sel:WORD_1
	v_cvt_f32_f16_e32 v36, v241
	v_cvt_f32_f16_sdwa v37, v241 dst_sel:DWORD dst_unused:UNUSED_PAD src0_sel:WORD_1
	v_sub_f32_e32 v34, v34, v242
	v_sub_f32_e32 v35, v35, v242
	v_sub_f32_e32 v36, v36, v242
	v_sub_f32_e32 v37, v37, v242
	v_pk_mul_f32 v[34:35], v[242:243], v[34:35] op_sel:[1,0]
	v_pk_mul_f32 v[36:37], v[242:243], v[36:37] op_sel:[1,0]
	v_pk_fma_f32 v[34:35], v[50:51], v[34:35], v[122:123]
	v_pk_fma_f32 v[36:37], v[52:53], v[36:37], v[124:125]
	v_pk_fma_f32 v[108:109], v[34:35], s[36:37], v[108:109] op_sel_hi:[1,0,1]
	v_pk_fma_f32 v[106:107], v[36:37], s[36:37], v[106:107] op_sel_hi:[1,0,1]
	s_nop 0
	v_cvt_pk_f16_f32 v107, v106, v107
	v_cvt_pk_f16_f32 v106, v108, v109
	global_store_dwordx2 v[32:33], v[106:107], off offset:288
	s_mov_b64 s[100:101], 0x40000
	v_lshl_add_u64 v[32:33], v[18:19], 0, s[100:101]
	s_waitcnt vmcnt(30)
	v_cvt_f32_f16_e32 v34, v158
	v_cvt_f32_f16_sdwa v35, v158 dst_sel:DWORD dst_unused:UNUSED_PAD src0_sel:WORD_1
	v_cvt_f32_f16_e32 v36, v159
	v_cvt_f32_f16_sdwa v37, v159 dst_sel:DWORD dst_unused:UNUSED_PAD src0_sel:WORD_1
	v_sub_f32_e32 v34, v34, v182
	v_sub_f32_e32 v35, v35, v182
	v_sub_f32_e32 v36, v36, v182
	v_sub_f32_e32 v37, v37, v182
	v_pk_mul_f32 v[34:35], v[182:183], v[34:35] op_sel:[1,0]
	v_pk_mul_f32 v[36:37], v[182:183], v[36:37] op_sel:[1,0]
	v_pk_fma_f32 v[34:35], v[38:39], v[34:35], v[58:59]
	v_pk_fma_f32 v[36:37], v[40:41], v[36:37], v[60:61]
	v_pk_fma_f32 v[104:105], v[34:35], s[36:37], v[104:105] op_sel_hi:[1,0,1]
	v_pk_fma_f32 v[102:103], v[36:37], s[36:37], v[102:103] op_sel_hi:[1,0,1]
	s_nop 0
	v_cvt_pk_f16_f32 v103, v102, v103
	v_cvt_pk_f16_f32 v102, v104, v105
	global_store_dwordx2 v[32:33], v[102:103], off
	s_waitcnt vmcnt(30)
	v_cvt_f32_f16_e32 v34, v160
	v_cvt_f32_f16_sdwa v35, v160 dst_sel:DWORD dst_unused:UNUSED_PAD src0_sel:WORD_1
	v_cvt_f32_f16_e32 v36, v161
	v_cvt_f32_f16_sdwa v37, v161 dst_sel:DWORD dst_unused:UNUSED_PAD src0_sel:WORD_1
	v_sub_f32_e32 v34, v34, v182
	v_sub_f32_e32 v35, v35, v182
	v_sub_f32_e32 v36, v36, v182
	v_sub_f32_e32 v37, v37, v182
	v_pk_mul_f32 v[34:35], v[182:183], v[34:35] op_sel:[1,0]
	v_pk_mul_f32 v[36:37], v[182:183], v[36:37] op_sel:[1,0]
	v_pk_fma_f32 v[34:35], v[42:43], v[34:35], v[66:67]
	v_pk_fma_f32 v[36:37], v[44:45], v[36:37], v[68:69]
	v_pk_fma_f32 v[100:101], v[34:35], s[36:37], v[100:101] op_sel_hi:[1,0,1]
	v_pk_fma_f32 v[98:99], v[36:37], s[36:37], v[98:99] op_sel_hi:[1,0,1]
	s_nop 0
	v_cvt_pk_f16_f32 v99, v98, v99
	v_cvt_pk_f16_f32 v98, v100, v101
	global_store_dwordx2 v[32:33], v[98:99], off offset:32
	s_waitcnt vmcnt(30)
	v_cvt_f32_f16_e32 v34, v170
	v_cvt_f32_f16_sdwa v35, v170 dst_sel:DWORD dst_unused:UNUSED_PAD src0_sel:WORD_1
	v_cvt_f32_f16_e32 v36, v171
	v_cvt_f32_f16_sdwa v37, v171 dst_sel:DWORD dst_unused:UNUSED_PAD src0_sel:WORD_1
	v_sub_f32_e32 v34, v34, v182
	v_sub_f32_e32 v35, v35, v182
	v_sub_f32_e32 v36, v36, v182
	v_sub_f32_e32 v37, v37, v182
	v_pk_mul_f32 v[34:35], v[182:183], v[34:35] op_sel:[1,0]
	v_pk_mul_f32 v[36:37], v[182:183], v[36:37] op_sel:[1,0]
	v_pk_fma_f32 v[34:35], v[46:47], v[34:35], v[74:75]
	v_pk_fma_f32 v[36:37], v[48:49], v[36:37], v[76:77]
	v_pk_fma_f32 v[96:97], v[34:35], s[36:37], v[96:97] op_sel_hi:[1,0,1]
	v_pk_fma_f32 v[94:95], v[36:37], s[36:37], v[94:95] op_sel_hi:[1,0,1]
	s_nop 0
	v_cvt_pk_f16_f32 v95, v94, v95
	v_cvt_pk_f16_f32 v94, v96, v97
	global_store_dwordx2 v[32:33], v[94:95], off offset:256
	s_waitcnt vmcnt(30)
	v_cvt_f32_f16_e32 v34, v176
	v_cvt_f32_f16_sdwa v35, v176 dst_sel:DWORD dst_unused:UNUSED_PAD src0_sel:WORD_1
	v_cvt_f32_f16_e32 v36, v177
	v_cvt_f32_f16_sdwa v37, v177 dst_sel:DWORD dst_unused:UNUSED_PAD src0_sel:WORD_1
	v_sub_f32_e32 v34, v34, v182
	v_sub_f32_e32 v35, v35, v182
	v_sub_f32_e32 v36, v36, v182
	v_sub_f32_e32 v37, v37, v182
	v_pk_mul_f32 v[34:35], v[182:183], v[34:35] op_sel:[1,0]
	v_pk_mul_f32 v[36:37], v[182:183], v[36:37] op_sel:[1,0]
	v_pk_fma_f32 v[34:35], v[50:51], v[34:35], v[122:123]
	v_pk_fma_f32 v[36:37], v[52:53], v[36:37], v[124:125]
	v_pk_fma_f32 v[92:93], v[34:35], s[36:37], v[92:93] op_sel_hi:[1,0,1]
	v_pk_fma_f32 v[90:91], v[36:37], s[36:37], v[90:91] op_sel_hi:[1,0,1]
	s_nop 0
	v_cvt_pk_f16_f32 v91, v90, v91
	v_cvt_pk_f16_f32 v90, v92, v93
	global_store_dwordx2 v[32:33], v[90:91], off offset:288
	s_mov_b64 s[100:101], 0x48000
	v_lshl_add_u64 v[32:33], v[18:19], 0, s[100:101]
	s_waitcnt vmcnt(29)
; __device__ __forceinline__ f32x4 ld4h(const ystream_t* p) { return __builtin_convertvector(*(const h16x4*)p, f32x4); }
; __device__ __forceinline__ void st4h(ystream_t* p, f32x4 v) { *(h16x4*)p = __builtin_convertvector(v, h16x4); }
;     __device__ __forceinline__ void operator()(const f32x4 (&acc)[2][2][4][2], const Unit& u, int wr, int wc, int fr, int fq) const {
;         const int row0 = u.pm * BM + wr * 64 + fr, colb = u.pn * BM + wc * 32 + 4 * fq;
; #pragma unroll
;         for (int ai = 0; ai < 2; ++ai)
; #pragma unroll
;             for (int m = 0; m < 4; ++m) {
;                 const int row = row0 + ai * HALF + m * 16;
;                 const float mu = st[(size_t)row * 32 + so], rs = st[(size_t)row * 32 + so + 1];
;                 const size_t off = (size_t)row * DM + colb;
; #pragma unroll
;                 for (int bj = 0; bj < 2; ++bj)
; #pragma unroll
;                     for (int n = 0; n < 2; ++n) { const int c = colb + bj * HALF + n * 16;
;                         const f32x4 gv = *(const f32x4*)(g + c), bv = *(const f32x4*)(b + c), yv = ld4h(Y + off + bj * HALF + n * 16);
;                         st4h(Y + off + bj * HALF + n * 16, ((yv - mu) * rs * gv + bv) * DN_ALPHA + acc[ai][bj][m][n] * asc); }
;                 asm volatile("" ::: "memory");
;             }
;     }
	v_cvt_f32_f16_e32 v34, v184
	v_cvt_f32_f16_sdwa v35, v184 dst_sel:DWORD dst_unused:UNUSED_PAD src0_sel:WORD_1
	v_cvt_f32_f16_e32 v36, v185
	v_cvt_f32_f16_sdwa v37, v185 dst_sel:DWORD dst_unused:UNUSED_PAD src0_sel:WORD_1
	v_sub_f32_e32 v34, v34, v192
	v_sub_f32_e32 v35, v35, v192
	v_sub_f32_e32 v36, v36, v192
	v_sub_f32_e32 v37, v37, v192
	v_pk_mul_f32 v[34:35], v[192:193], v[34:35] op_sel:[1,0]
	v_pk_mul_f32 v[36:37], v[192:193], v[36:37] op_sel:[1,0]
	v_pk_fma_f32 v[34:35], v[38:39], v[34:35], v[58:59]
	v_pk_fma_f32 v[36:37], v[40:41], v[36:37], v[60:61]
	v_pk_fma_f32 v[86:87], v[34:35], s[36:37], v[86:87] op_sel_hi:[1,0,1]
	v_pk_fma_f32 v[88:89], v[36:37], s[36:37], v[88:89] op_sel_hi:[1,0,1]
	s_nop 0
	v_cvt_pk_f16_f32 v89, v88, v89
	v_cvt_pk_f16_f32 v88, v86, v87
	global_store_dwordx2 v[32:33], v[88:89], off
	s_waitcnt vmcnt(29)
	v_cvt_f32_f16_e32 v34, v186
	v_cvt_f32_f16_sdwa v35, v186 dst_sel:DWORD dst_unused:UNUSED_PAD src0_sel:WORD_1
	v_cvt_f32_f16_e32 v36, v187
	v_cvt_f32_f16_sdwa v37, v187 dst_sel:DWORD dst_unused:UNUSED_PAD src0_sel:WORD_1
	v_sub_f32_e32 v34, v34, v192
	v_sub_f32_e32 v35, v35, v192
	v_sub_f32_e32 v36, v36, v192
	v_sub_f32_e32 v37, v37, v192
	v_pk_mul_f32 v[34:35], v[192:193], v[34:35] op_sel:[1,0]
	v_pk_mul_f32 v[36:37], v[192:193], v[36:37] op_sel:[1,0]
	v_pk_fma_f32 v[34:35], v[42:43], v[34:35], v[66:67]
	v_pk_fma_f32 v[36:37], v[44:45], v[36:37], v[68:69]
	v_pk_fma_f32 v[82:83], v[34:35], s[36:37], v[82:83] op_sel_hi:[1,0,1]
	v_pk_fma_f32 v[84:85], v[36:37], s[36:37], v[84:85] op_sel_hi:[1,0,1]
	s_nop 0
	v_cvt_pk_f16_f32 v85, v84, v85
	v_cvt_pk_f16_f32 v84, v82, v83
	global_store_dwordx2 v[32:33], v[84:85], off offset:32
	s_waitcnt vmcnt(29)
	v_cvt_f32_f16_e32 v34, v188
	v_cvt_f32_f16_sdwa v35, v188 dst_sel:DWORD dst_unused:UNUSED_PAD src0_sel:WORD_1
	v_cvt_f32_f16_e32 v36, v189
	v_cvt_f32_f16_sdwa v37, v189 dst_sel:DWORD dst_unused:UNUSED_PAD src0_sel:WORD_1
	v_sub_f32_e32 v34, v34, v192
	v_sub_f32_e32 v35, v35, v192
	v_sub_f32_e32 v36, v36, v192
	v_sub_f32_e32 v37, v37, v192
	v_pk_mul_f32 v[34:35], v[192:193], v[34:35] op_sel:[1,0]
	v_pk_mul_f32 v[36:37], v[192:193], v[36:37] op_sel:[1,0]
	v_pk_fma_f32 v[34:35], v[46:47], v[34:35], v[74:75]
	v_pk_fma_f32 v[36:37], v[48:49], v[36:37], v[76:77]
	v_pk_fma_f32 v[80:81], v[34:35], s[36:37], v[80:81] op_sel_hi:[1,0,1]
	v_pk_fma_f32 v[78:79], v[36:37], s[36:37], v[78:79] op_sel_hi:[1,0,1]
	s_nop 0
	v_cvt_pk_f16_f32 v79, v78, v79
	v_cvt_pk_f16_f32 v78, v80, v81
	global_store_dwordx2 v[32:33], v[78:79], off offset:256
	s_waitcnt vmcnt(29)
	v_cvt_f32_f16_e32 v34, v190
	v_cvt_f32_f16_sdwa v35, v190 dst_sel:DWORD dst_unused:UNUSED_PAD src0_sel:WORD_1
	v_cvt_f32_f16_e32 v36, v191
	v_cvt_f32_f16_sdwa v37, v191 dst_sel:DWORD dst_unused:UNUSED_PAD src0_sel:WORD_1
	v_sub_f32_e32 v34, v34, v192
	v_sub_f32_e32 v35, v35, v192
	v_sub_f32_e32 v36, v36, v192
	v_sub_f32_e32 v37, v37, v192
	v_pk_mul_f32 v[34:35], v[192:193], v[34:35] op_sel:[1,0]
	v_pk_mul_f32 v[36:37], v[192:193], v[36:37] op_sel:[1,0]
	v_pk_fma_f32 v[34:35], v[50:51], v[34:35], v[122:123]
	v_pk_fma_f32 v[36:37], v[52:53], v[36:37], v[124:125]
	v_pk_fma_f32 v[72:73], v[34:35], s[36:37], v[72:73] op_sel_hi:[1,0,1]
	v_pk_fma_f32 v[70:71], v[36:37], s[36:37], v[70:71] op_sel_hi:[1,0,1]
	s_nop 0
	v_cvt_pk_f16_f32 v71, v70, v71
	v_cvt_pk_f16_f32 v70, v72, v73
	global_store_dwordx2 v[32:33], v[70:71], off offset:288
	s_mov_b64 s[100:101], 0x50000
	v_lshl_add_u64 v[32:33], v[18:19], 0, s[100:101]
	s_waitcnt vmcnt(28)
	v_cvt_f32_f16_e32 v34, v208
	v_cvt_f32_f16_sdwa v35, v208 dst_sel:DWORD dst_unused:UNUSED_PAD src0_sel:WORD_1
	v_cvt_f32_f16_e32 v36, v209
	v_cvt_f32_f16_sdwa v37, v209 dst_sel:DWORD dst_unused:UNUSED_PAD src0_sel:WORD_1
	v_sub_f32_e32 v34, v34, v246
	v_sub_f32_e32 v35, v35, v246
	v_sub_f32_e32 v36, v36, v246
	v_sub_f32_e32 v37, v37, v246
	v_pk_mul_f32 v[34:35], v[246:247], v[34:35] op_sel:[1,0]
	v_pk_mul_f32 v[36:37], v[246:247], v[36:37] op_sel:[1,0]
	v_pk_fma_f32 v[34:35], v[38:39], v[34:35], v[58:59]
	v_pk_fma_f32 v[36:37], v[40:41], v[36:37], v[60:61]
	v_pk_fma_f32 v[64:65], v[34:35], s[36:37], v[64:65] op_sel_hi:[1,0,1]
	v_pk_fma_f32 v[62:63], v[36:37], s[36:37], v[62:63] op_sel_hi:[1,0,1]
	s_nop 0
	v_cvt_pk_f16_f32 v63, v62, v63
	v_cvt_pk_f16_f32 v62, v64, v65
	global_store_dwordx2 v[32:33], v[62:63], off
	s_waitcnt vmcnt(28)
	v_cvt_f32_f16_e32 v34, v210
	v_cvt_f32_f16_sdwa v35, v210 dst_sel:DWORD dst_unused:UNUSED_PAD src0_sel:WORD_1
	v_cvt_f32_f16_e32 v36, v211
	v_cvt_f32_f16_sdwa v37, v211 dst_sel:DWORD dst_unused:UNUSED_PAD src0_sel:WORD_1
	v_sub_f32_e32 v34, v34, v246
	v_sub_f32_e32 v35, v35, v246
	v_sub_f32_e32 v36, v36, v246
	v_sub_f32_e32 v37, v37, v246
	v_pk_mul_f32 v[34:35], v[246:247], v[34:35] op_sel:[1,0]
	v_pk_mul_f32 v[36:37], v[246:247], v[36:37] op_sel:[1,0]
	v_pk_fma_f32 v[34:35], v[42:43], v[34:35], v[66:67]
	v_pk_fma_f32 v[36:37], v[44:45], v[36:37], v[68:69]
	v_pk_fma_f32 v[56:57], v[34:35], s[36:37], v[56:57] op_sel_hi:[1,0,1]
	v_pk_fma_f32 v[54:55], v[36:37], s[36:37], v[54:55] op_sel_hi:[1,0,1]
	s_nop 0
	v_cvt_pk_f16_f32 v55, v54, v55
	v_cvt_pk_f16_f32 v54, v56, v57
	global_store_dwordx2 v[32:33], v[54:55], off offset:32
	s_waitcnt vmcnt(28)
; __device__ __forceinline__ f32x4 ld4h(const ystream_t* p) { return __builtin_convertvector(*(const h16x4*)p, f32x4); }
; __device__ __forceinline__ void st4h(ystream_t* p, f32x4 v) { *(h16x4*)p = __builtin_convertvector(v, h16x4); }
;     __device__ __forceinline__ void operator()(const f32x4 (&acc)[2][2][4][2], const Unit& u, int wr, int wc, int fr, int fq) const {
;         const int row0 = u.pm * BM + wr * 64 + fr, colb = u.pn * BM + wc * 32 + 4 * fq;
; #pragma unroll
;         for (int ai = 0; ai < 2; ++ai)
; #pragma unroll
;             for (int m = 0; m < 4; ++m) {
;                 const int row = row0 + ai * HALF + m * 16;
;                 const float mu = st[(size_t)row * 32 + so], rs = st[(size_t)row * 32 + so + 1];
;                 const size_t off = (size_t)row * DM + colb;
; #pragma unroll
;                 for (int bj = 0; bj < 2; ++bj)
; #pragma unroll
;                     for (int n = 0; n < 2; ++n) { const int c = colb + bj * HALF + n * 16;
;                         const f32x4 gv = *(const f32x4*)(g + c), bv = *(const f32x4*)(b + c), yv = ld4h(Y + off + bj * HALF + n * 16);
;                         st4h(Y + off + bj * HALF + n * 16, ((yv - mu) * rs * gv + bv) * DN_ALPHA + acc[ai][bj][m][n] * asc); }
;                 asm volatile("" ::: "memory");
;             }
;     }
	v_cvt_f32_f16_e32 v34, v212
	v_cvt_f32_f16_sdwa v35, v212 dst_sel:DWORD dst_unused:UNUSED_PAD src0_sel:WORD_1
	v_cvt_f32_f16_e32 v36, v213
	v_cvt_f32_f16_sdwa v37, v213 dst_sel:DWORD dst_unused:UNUSED_PAD src0_sel:WORD_1
	v_sub_f32_e32 v34, v34, v246
	v_sub_f32_e32 v35, v35, v246
	v_sub_f32_e32 v36, v36, v246
	v_sub_f32_e32 v37, v37, v246
	v_pk_mul_f32 v[34:35], v[246:247], v[34:35] op_sel:[1,0]
	v_pk_mul_f32 v[36:37], v[246:247], v[36:37] op_sel:[1,0]
	v_pk_fma_f32 v[34:35], v[46:47], v[34:35], v[74:75]
	v_pk_fma_f32 v[36:37], v[48:49], v[36:37], v[76:77]
	v_pk_fma_f32 v[28:29], v[34:35], s[36:37], v[28:29] op_sel_hi:[1,0,1]
	v_pk_fma_f32 v[26:27], v[36:37], s[36:37], v[26:27] op_sel_hi:[1,0,1]
	s_nop 0
	v_cvt_pk_f16_f32 v27, v26, v27
	v_cvt_pk_f16_f32 v26, v28, v29
	global_store_dwordx2 v[32:33], v[26:27], off offset:256
	s_waitcnt vmcnt(28)
	v_cvt_f32_f16_e32 v34, v244
	v_cvt_f32_f16_sdwa v35, v244 dst_sel:DWORD dst_unused:UNUSED_PAD src0_sel:WORD_1
	v_cvt_f32_f16_e32 v36, v245
	v_cvt_f32_f16_sdwa v37, v245 dst_sel:DWORD dst_unused:UNUSED_PAD src0_sel:WORD_1
	v_sub_f32_e32 v34, v34, v246
	v_sub_f32_e32 v35, v35, v246
	v_sub_f32_e32 v36, v36, v246
	v_sub_f32_e32 v37, v37, v246
	v_pk_mul_f32 v[34:35], v[246:247], v[34:35] op_sel:[1,0]
	v_pk_mul_f32 v[36:37], v[246:247], v[36:37] op_sel:[1,0]
	v_pk_fma_f32 v[34:35], v[50:51], v[34:35], v[122:123]
	v_pk_fma_f32 v[36:37], v[52:53], v[36:37], v[124:125]
	v_pk_fma_f32 v[24:25], v[34:35], s[36:37], v[24:25] op_sel_hi:[1,0,1]
	v_pk_fma_f32 v[22:23], v[36:37], s[36:37], v[22:23] op_sel_hi:[1,0,1]
	s_nop 0
	v_cvt_pk_f16_f32 v23, v22, v23
	v_cvt_pk_f16_f32 v22, v24, v25
	global_store_dwordx2 v[32:33], v[22:23], off offset:288
	s_mov_b64 s[100:101], 0x58000
	v_lshl_add_u64 v[32:33], v[18:19], 0, s[100:101]
	s_waitcnt vmcnt(23)
	v_cvt_f32_f16_e32 v34, v142
	v_cvt_f32_f16_sdwa v35, v142 dst_sel:DWORD dst_unused:UNUSED_PAD src0_sel:WORD_1
	v_cvt_f32_f16_e32 v36, v143
	v_cvt_f32_f16_sdwa v37, v143 dst_sel:DWORD dst_unused:UNUSED_PAD src0_sel:WORD_1
	v_sub_f32_e32 v34, v34, v150
	v_sub_f32_e32 v35, v35, v150
	v_sub_f32_e32 v36, v36, v150
	v_sub_f32_e32 v37, v37, v150
	v_pk_mul_f32 v[34:35], v[150:151], v[34:35] op_sel:[1,0]
	v_pk_mul_f32 v[36:37], v[150:151], v[36:37] op_sel:[1,0]
	v_pk_fma_f32 v[34:35], v[38:39], v[34:35], v[58:59]
	v_pk_fma_f32 v[36:37], v[40:41], v[36:37], v[60:61]
	v_pk_fma_f32 v[16:17], v[34:35], s[36:37], v[16:17] op_sel_hi:[1,0,1]
	v_pk_fma_f32 v[14:15], v[36:37], s[36:37], v[14:15] op_sel_hi:[1,0,1]
	s_nop 0
	v_cvt_pk_f16_f32 v15, v14, v15
	v_cvt_pk_f16_f32 v14, v16, v17
	global_store_dwordx2 v[32:33], v[14:15], off
	s_waitcnt vmcnt(23)
	v_cvt_f32_f16_e32 v34, v144
	v_cvt_f32_f16_sdwa v35, v144 dst_sel:DWORD dst_unused:UNUSED_PAD src0_sel:WORD_1
	v_cvt_f32_f16_e32 v36, v145
	v_cvt_f32_f16_sdwa v37, v145 dst_sel:DWORD dst_unused:UNUSED_PAD src0_sel:WORD_1
	v_sub_f32_e32 v34, v34, v150
	v_sub_f32_e32 v35, v35, v150
	v_sub_f32_e32 v36, v36, v150
	v_sub_f32_e32 v37, v37, v150
	v_pk_mul_f32 v[34:35], v[150:151], v[34:35] op_sel:[1,0]
	v_pk_mul_f32 v[36:37], v[150:151], v[36:37] op_sel:[1,0]
	v_pk_fma_f32 v[34:35], v[42:43], v[34:35], v[66:67]
	v_pk_fma_f32 v[36:37], v[44:45], v[36:37], v[68:69]
	v_pk_fma_f32 v[8:9], v[34:35], s[36:37], v[8:9] op_sel_hi:[1,0,1]
	v_pk_fma_f32 v[6:7], v[36:37], s[36:37], v[6:7] op_sel_hi:[1,0,1]
	s_nop 0
	v_cvt_pk_f16_f32 v7, v6, v7
	v_cvt_pk_f16_f32 v6, v8, v9
	global_store_dwordx2 v[32:33], v[6:7], off offset:32
	s_waitcnt vmcnt(23)
	v_cvt_f32_f16_e32 v34, v146
	v_cvt_f32_f16_sdwa v35, v146 dst_sel:DWORD dst_unused:UNUSED_PAD src0_sel:WORD_1
	v_cvt_f32_f16_e32 v36, v147
	v_cvt_f32_f16_sdwa v37, v147 dst_sel:DWORD dst_unused:UNUSED_PAD src0_sel:WORD_1
	v_sub_f32_e32 v34, v34, v150
	v_sub_f32_e32 v35, v35, v150
	v_sub_f32_e32 v36, v36, v150
	v_sub_f32_e32 v37, v37, v150
	v_pk_mul_f32 v[34:35], v[150:151], v[34:35] op_sel:[1,0]
	v_pk_mul_f32 v[36:37], v[150:151], v[36:37] op_sel:[1,0]
	v_pk_fma_f32 v[34:35], v[46:47], v[34:35], v[74:75]
	v_pk_fma_f32 v[36:37], v[48:49], v[36:37], v[76:77]
	v_pk_fma_f32 v[4:5], v[34:35], s[36:37], v[4:5] op_sel_hi:[1,0,1]
	v_pk_fma_f32 v[2:3], v[36:37], s[36:37], v[2:3] op_sel_hi:[1,0,1]
	s_nop 0
	v_cvt_pk_f16_f32 v3, v2, v3
	v_cvt_pk_f16_f32 v2, v4, v5
	global_store_dwordx2 v[32:33], v[2:3], off offset:256
	s_waitcnt vmcnt(23)
	v_cvt_f32_f16_e32 v34, v148
	v_cvt_f32_f16_sdwa v35, v148 dst_sel:DWORD dst_unused:UNUSED_PAD src0_sel:WORD_1
	v_cvt_f32_f16_e32 v36, v149
	v_cvt_f32_f16_sdwa v37, v149 dst_sel:DWORD dst_unused:UNUSED_PAD src0_sel:WORD_1
	v_sub_f32_e32 v34, v34, v150
	v_sub_f32_e32 v35, v35, v150
	v_sub_f32_e32 v36, v36, v150
	v_sub_f32_e32 v37, v37, v150
	v_pk_mul_f32 v[34:35], v[150:151], v[34:35] op_sel:[1,0]
	v_pk_mul_f32 v[36:37], v[150:151], v[36:37] op_sel:[1,0]
	v_pk_fma_f32 v[34:35], v[50:51], v[34:35], v[122:123]
	v_pk_fma_f32 v[36:37], v[52:53], v[36:37], v[124:125]
	v_pk_fma_f32 v[12:13], v[34:35], s[36:37], v[12:13] op_sel_hi:[1,0,1]
	v_pk_fma_f32 v[10:11], v[36:37], s[36:37], v[10:11] op_sel_hi:[1,0,1]
	s_nop 0
	v_cvt_pk_f16_f32 v11, v10, v11
	v_cvt_pk_f16_f32 v10, v12, v13
	global_store_dwordx2 v[32:33], v[10:11], off offset:288
	s_mov_b64 s[2:3], -1
	s_and_b64 vcc, exec, s[42:43]
	s_cbranch_vccnz .LBB0_1601
	s_andn2_b64 vcc, exec, s[0:1]
	s_cbranch_vccnz .LBB0_1600
	s_barrier
	s_branch .LBB0_1600
